# 4th GEMM loop (K=4096/5632 resid GEMMs) fully converted to SGPR-base LDS-DMA using free SGPRs s68-s71 + ds_read base hoist
# speedup vs baseline: 1.0367x; 1.0040x over previous
.LBB0_245:
	s_add_u32 s10, s10, 0x80
	s_addc_u32 s11, s11, 0
	s_add_u32 s42, s12, 0x100
	s_addc_u32 s43, s13, 0
	s_mov_b32 s12, 0
	s_mov_b64 s[48:49], 0x80
	v_readlane_b32 s52, v254, 14
	v_readlane_b32 s53, v254, 15
	v_readlane_b32 s54, v254, 16
	v_readlane_b32 s55, v254, 17
	v_add_u32_e32 v218, 0x10000, v191
	s_add_i32 s44, s12, 2
	s_add_u32 s14, s10, 0x80
	s_addc_u32 s13, s11, 0
	s_add_i32 s45, 0, 0x10000
	ds_read_b128 v[120:123], v218 offset:0
	ds_read_b128 v[124:127], v218 offset:1024
	ds_read_b128 v[128:131], v218 offset:2048
	ds_read_b128 v[132:135], v218 offset:3072
	s_cmp_eq_u32 s36, s12
	s_cselect_b32 s12, s4, s14
	s_cselect_b32 s13, s5, s13
	s_cselect_b32 s15, s7, s43
	s_cselect_b32 s14, s6, s42
	s_add_i32 m0, s26, 0xc000
	ds_read_b128 v[144:147], v205
	ds_read_b128 v[148:151], v205 offset:1024
	ds_read_b128 v[152:155], v205 offset:2048
	ds_read_b128 v[156:159], v205 offset:3072
	ds_read_b128 v[160:163], v205 offset:4096
	ds_read_b128 v[164:167], v205 offset:5120
	ds_read_b128 v[178:181], v205 offset:6144
	ds_read_b128 v[182:185], v205 offset:7168
	global_load_lds_dwordx4 v174, s[10:11]
	s_add_i32 m0, s26, 0xe000
	s_nop 0
	global_load_lds_dwordx4 v176, s[10:11]
	s_waitcnt lgkmcnt(8)
	s_barrier
	s_waitcnt lgkmcnt(0)
	v_mfma_f32_16x16x32_bf16 v[140:143], v[120:123], v[144:147], 0
	v_mfma_f32_16x16x32_bf16 v[136:139], v[128:131], v[144:147], 0
	v_mfma_f32_16x16x32_bf16 v[108:111], v[120:123], v[152:155], 0
	v_mfma_f32_16x16x32_bf16 v[104:107], v[128:131], v[152:155], 0
	v_mfma_f32_16x16x32_bf16 v[92:95], v[120:123], v[160:163], 0
	v_mfma_f32_16x16x32_bf16 v[88:91], v[128:131], v[160:163], 0
	v_mfma_f32_16x16x32_bf16 v[76:79], v[120:123], v[178:181], 0
	v_mfma_f32_16x16x32_bf16 v[72:75], v[128:131], v[178:181], 0
	v_mfma_f32_16x16x32_bf16 v[140:143], v[124:127], v[148:151], v[140:143]
	v_mfma_f32_16x16x32_bf16 v[136:139], v[132:135], v[148:151], v[136:139]
	v_mfma_f32_16x16x32_bf16 v[108:111], v[124:127], v[156:159], v[108:111]
	v_mfma_f32_16x16x32_bf16 v[104:107], v[132:135], v[156:159], v[104:107]
	v_mfma_f32_16x16x32_bf16 v[92:95], v[124:127], v[164:167], v[92:95]
	v_mfma_f32_16x16x32_bf16 v[88:91], v[132:135], v[164:167], v[88:91]
	v_mfma_f32_16x16x32_bf16 v[76:79], v[124:127], v[182:185], v[76:79]
	v_mfma_f32_16x16x32_bf16 v[72:75], v[132:135], v[182:185], v[72:75]
	s_barrier
	s_add_i32 s46, 0, 0x14000
	s_add_i32 s45, s45, s25
	ds_read_b128 v[186:189], v218 offset:16384
	ds_read_b128 v[196:199], v218 offset:17408
	ds_read_b128 v[206:209], v218 offset:18432
	ds_read_b128 v[214:217], v218 offset:19456
	s_add_u32 s68, s14, 0x80
	s_addc_u32 s69, s15, 0
	s_mov_b32 m0, s45
	s_nop 0
	global_load_lds_dwordx4 v192, s[14:15]
	s_add_i32 m0, s45, 0x2000
	s_nop 0
	global_load_lds_dwordx4 v172, s[14:15]
	s_barrier
	s_waitcnt lgkmcnt(0)
	v_mfma_f32_16x16x32_bf16 v[116:119], v[186:189], v[144:147], 0
	v_mfma_f32_16x16x32_bf16 v[112:115], v[206:209], v[144:147], 0
	v_mfma_f32_16x16x32_bf16 v[100:103], v[186:189], v[152:155], 0
	v_mfma_f32_16x16x32_bf16 v[96:99], v[206:209], v[152:155], 0
	v_mfma_f32_16x16x32_bf16 v[84:87], v[186:189], v[160:163], 0
	v_mfma_f32_16x16x32_bf16 v[80:83], v[206:209], v[160:163], 0
	v_mfma_f32_16x16x32_bf16 v[68:71], v[186:189], v[178:181], 0
	v_mfma_f32_16x16x32_bf16 v[64:67], v[206:209], v[178:181], 0
	v_mfma_f32_16x16x32_bf16 v[116:119], v[196:199], v[148:151], v[116:119]
	v_mfma_f32_16x16x32_bf16 v[112:115], v[214:217], v[148:151], v[112:115]
	v_mfma_f32_16x16x32_bf16 v[100:103], v[196:199], v[156:159], v[100:103]
	v_mfma_f32_16x16x32_bf16 v[96:99], v[214:217], v[156:159], v[96:99]
	v_mfma_f32_16x16x32_bf16 v[84:87], v[196:199], v[164:167], v[84:87]
	v_mfma_f32_16x16x32_bf16 v[80:83], v[214:217], v[164:167], v[80:83]
	v_mfma_f32_16x16x32_bf16 v[68:71], v[196:199], v[182:185], v[68:71]
	v_mfma_f32_16x16x32_bf16 v[64:67], v[214:217], v[182:185], v[64:67]
	s_mov_b32 m0, s26
	s_add_u32 s70, s12, 0x80
	s_addc_u32 s71, s13, 0
	s_barrier
	ds_read_b128 v[144:147], v205 offset:16384
	ds_read_b128 v[148:151], v205 offset:17408
	ds_read_b128 v[152:155], v205 offset:18432
	ds_read_b128 v[156:159], v205 offset:19456
	ds_read_b128 v[160:163], v205 offset:20480
	ds_read_b128 v[164:167], v205 offset:21504
	ds_read_b128 v[178:181], v205 offset:22528
	ds_read_b128 v[182:185], v205 offset:23552
	global_load_lds_dwordx4 v168, s[12:13]
	s_mov_b32 m0, s27
	s_nop 0
	global_load_lds_dwordx4 v170, s[12:13]
	s_barrier
	s_waitcnt lgkmcnt(0)
	v_mfma_f32_16x16x32_bf16 v[60:63], v[120:123], v[144:147], 0
	v_mfma_f32_16x16x32_bf16 v[56:59], v[128:131], v[144:147], 0
	v_mfma_f32_16x16x32_bf16 v[44:47], v[120:123], v[152:155], 0
	v_mfma_f32_16x16x32_bf16 v[40:43], v[128:131], v[152:155], 0
	v_mfma_f32_16x16x32_bf16 v[28:31], v[120:123], v[160:163], 0
	v_mfma_f32_16x16x32_bf16 v[24:27], v[128:131], v[160:163], 0
	v_mfma_f32_16x16x32_bf16 v[12:15], v[120:123], v[178:181], 0
	v_mfma_f32_16x16x32_bf16 v[8:11], v[128:131], v[178:181], 0
	v_mfma_f32_16x16x32_bf16 v[60:63], v[124:127], v[148:151], v[60:63]
	v_mfma_f32_16x16x32_bf16 v[56:59], v[132:135], v[148:151], v[56:59]
	v_mfma_f32_16x16x32_bf16 v[44:47], v[124:127], v[156:159], v[44:47]
	v_mfma_f32_16x16x32_bf16 v[40:43], v[132:135], v[156:159], v[40:43]
	v_mfma_f32_16x16x32_bf16 v[28:31], v[124:127], v[164:167], v[28:31]
	v_mfma_f32_16x16x32_bf16 v[24:27], v[132:135], v[164:167], v[24:27]
	v_mfma_f32_16x16x32_bf16 v[12:15], v[124:127], v[182:185], v[12:15]
	v_mfma_f32_16x16x32_bf16 v[8:11], v[132:135], v[182:185], v[8:11]
	s_barrier
	s_add_u32 s14, s14, s52
	s_addc_u32 s15, s15, 0
	s_add_i32 s45, s46, s25
	s_mov_b32 m0, s45
	s_nop 0
	global_load_lds_dwordx4 v192, s[14:15]
	s_add_i32 m0, s45, 0x2000
	s_nop 0
	global_load_lds_dwordx4 v172, s[14:15]
	s_waitcnt vmcnt(6)
	s_barrier
	v_mfma_f32_16x16x32_bf16 v[52:55], v[186:189], v[144:147], 0
	v_mfma_f32_16x16x32_bf16 v[48:51], v[206:209], v[144:147], 0
	v_mfma_f32_16x16x32_bf16 v[36:39], v[186:189], v[152:155], 0
	v_mfma_f32_16x16x32_bf16 v[32:35], v[206:209], v[152:155], 0
	v_mfma_f32_16x16x32_bf16 v[20:23], v[186:189], v[160:163], 0
	v_mfma_f32_16x16x32_bf16 v[16:19], v[206:209], v[160:163], 0
	v_mfma_f32_16x16x32_bf16 v[4:7], v[186:189], v[178:181], 0
	v_mfma_f32_16x16x32_bf16 v[0:3], v[206:209], v[178:181], 0
	v_mfma_f32_16x16x32_bf16 v[52:55], v[196:199], v[148:151], v[52:55]
	v_mfma_f32_16x16x32_bf16 v[48:51], v[214:217], v[148:151], v[48:51]
	v_mfma_f32_16x16x32_bf16 v[36:39], v[196:199], v[156:159], v[36:39]
	v_mfma_f32_16x16x32_bf16 v[32:35], v[214:217], v[156:159], v[32:35]
	v_mfma_f32_16x16x32_bf16 v[20:23], v[196:199], v[164:167], v[20:23]
	v_mfma_f32_16x16x32_bf16 v[16:19], v[214:217], v[164:167], v[16:19]
	v_mfma_f32_16x16x32_bf16 v[4:7], v[196:199], v[182:185], v[4:7]
	v_mfma_f32_16x16x32_bf16 v[0:3], v[214:217], v[182:185], v[0:3]
	s_add_i32 s14, 0, 0x18000
	s_barrier
	ds_read_b128 v[120:123], v218 offset:32768
	ds_read_b128 v[124:127], v218 offset:33792
	ds_read_b128 v[128:131], v218 offset:34816
	ds_read_b128 v[132:135], v218 offset:35840
	s_add_u32 s12, s12, s52
	s_addc_u32 s13, s13, 0
	s_mov_b32 m0, s28
	ds_read_b128 v[144:147], v205 offset:32768
	ds_read_b128 v[148:151], v205 offset:33792
	ds_read_b128 v[152:155], v205 offset:34816
	ds_read_b128 v[156:159], v205 offset:35840
	ds_read_b128 v[160:163], v205 offset:36864
	ds_read_b128 v[164:167], v205 offset:37888
	ds_read_b128 v[178:181], v205 offset:38912
	ds_read_b128 v[182:185], v205 offset:39936
	global_load_lds_dwordx4 v168, s[12:13]
	s_mov_b32 m0, s29
	s_nop 0
	global_load_lds_dwordx4 v170, s[12:13]
	s_waitcnt lgkmcnt(8)
	s_barrier
	s_waitcnt lgkmcnt(0)
	v_mfma_f32_16x16x32_bf16 v[140:143], v[120:123], v[144:147], v[140:143]
	v_mfma_f32_16x16x32_bf16 v[136:139], v[128:131], v[144:147], v[136:139]
	v_mfma_f32_16x16x32_bf16 v[108:111], v[120:123], v[152:155], v[108:111]
	v_mfma_f32_16x16x32_bf16 v[104:107], v[128:131], v[152:155], v[104:107]
	v_mfma_f32_16x16x32_bf16 v[92:95], v[120:123], v[160:163], v[92:95]
	v_mfma_f32_16x16x32_bf16 v[88:91], v[128:131], v[160:163], v[88:91]
	v_mfma_f32_16x16x32_bf16 v[76:79], v[120:123], v[178:181], v[76:79]
	v_mfma_f32_16x16x32_bf16 v[72:75], v[128:131], v[178:181], v[72:75]
	v_mfma_f32_16x16x32_bf16 v[140:143], v[124:127], v[148:151], v[140:143]
	v_mfma_f32_16x16x32_bf16 v[136:139], v[132:135], v[148:151], v[136:139]
	v_mfma_f32_16x16x32_bf16 v[108:111], v[124:127], v[156:159], v[108:111]
	v_mfma_f32_16x16x32_bf16 v[104:107], v[132:135], v[156:159], v[104:107]
	v_mfma_f32_16x16x32_bf16 v[92:95], v[124:127], v[164:167], v[92:95]
	v_mfma_f32_16x16x32_bf16 v[88:91], v[132:135], v[164:167], v[88:91]
	v_mfma_f32_16x16x32_bf16 v[76:79], v[124:127], v[182:185], v[76:79]
	v_mfma_f32_16x16x32_bf16 v[72:75], v[132:135], v[182:185], v[72:75]
	s_barrier
	s_add_i32 s12, 0, 0x1c000
	s_add_i32 s13, s14, s25
	s_mov_b32 m0, s13
	ds_read_b128 v[186:189], v218 offset:49152
	ds_read_b128 v[196:199], v218 offset:50176
	ds_read_b128 v[206:209], v218 offset:51200
	ds_read_b128 v[214:217], v218 offset:52224
	global_load_lds_dwordx4 v192, s[68:69]
	s_add_i32 m0, s13, 0x2000
	s_nop 0
	global_load_lds_dwordx4 v172, s[68:69]
	s_barrier
	s_waitcnt lgkmcnt(0)
	v_mfma_f32_16x16x32_bf16 v[116:119], v[186:189], v[144:147], v[116:119]
	v_mfma_f32_16x16x32_bf16 v[112:115], v[206:209], v[144:147], v[112:115]
	v_mfma_f32_16x16x32_bf16 v[100:103], v[186:189], v[152:155], v[100:103]
	v_mfma_f32_16x16x32_bf16 v[96:99], v[206:209], v[152:155], v[96:99]
	v_mfma_f32_16x16x32_bf16 v[84:87], v[186:189], v[160:163], v[84:87]
	v_mfma_f32_16x16x32_bf16 v[80:83], v[206:209], v[160:163], v[80:83]
	v_mfma_f32_16x16x32_bf16 v[68:71], v[186:189], v[178:181], v[68:71]
	v_mfma_f32_16x16x32_bf16 v[64:67], v[206:209], v[178:181], v[64:67]
	v_mfma_f32_16x16x32_bf16 v[116:119], v[196:199], v[148:151], v[116:119]
	v_mfma_f32_16x16x32_bf16 v[112:115], v[214:217], v[148:151], v[112:115]
	v_mfma_f32_16x16x32_bf16 v[100:103], v[196:199], v[156:159], v[100:103]
	v_mfma_f32_16x16x32_bf16 v[96:99], v[214:217], v[156:159], v[96:99]
	v_mfma_f32_16x16x32_bf16 v[84:87], v[196:199], v[164:167], v[84:87]
	v_mfma_f32_16x16x32_bf16 v[80:83], v[214:217], v[164:167], v[80:83]
	v_mfma_f32_16x16x32_bf16 v[68:71], v[196:199], v[182:185], v[68:71]
	v_mfma_f32_16x16x32_bf16 v[64:67], v[214:217], v[182:185], v[64:67]
	s_mov_b32 m0, s34
	s_barrier
	ds_read_b128 v[144:147], v205 offset:49152
	ds_read_b128 v[148:151], v205 offset:50176
	ds_read_b128 v[152:155], v205 offset:51200
	ds_read_b128 v[156:159], v205 offset:52224
	ds_read_b128 v[160:163], v205 offset:53248
	ds_read_b128 v[164:167], v205 offset:54272
	ds_read_b128 v[178:181], v205 offset:55296
	ds_read_b128 v[182:185], v205 offset:56320
	global_load_lds_dwordx4 v168, s[70:71]
	s_mov_b32 m0, s35
	s_nop 0
	global_load_lds_dwordx4 v170, s[70:71]
	s_barrier
	s_waitcnt lgkmcnt(0)
	v_mfma_f32_16x16x32_bf16 v[60:63], v[120:123], v[144:147], v[60:63]
	v_mfma_f32_16x16x32_bf16 v[56:59], v[128:131], v[144:147], v[56:59]
	v_mfma_f32_16x16x32_bf16 v[44:47], v[120:123], v[152:155], v[44:47]
	v_mfma_f32_16x16x32_bf16 v[40:43], v[128:131], v[152:155], v[40:43]
	v_mfma_f32_16x16x32_bf16 v[28:31], v[120:123], v[160:163], v[28:31]
	v_mfma_f32_16x16x32_bf16 v[24:27], v[128:131], v[160:163], v[24:27]
	v_mfma_f32_16x16x32_bf16 v[12:15], v[120:123], v[178:181], v[12:15]
	v_mfma_f32_16x16x32_bf16 v[8:11], v[128:131], v[178:181], v[8:11]
	v_mfma_f32_16x16x32_bf16 v[60:63], v[124:127], v[148:151], v[60:63]
	v_mfma_f32_16x16x32_bf16 v[56:59], v[132:135], v[148:151], v[56:59]
	v_mfma_f32_16x16x32_bf16 v[44:47], v[124:127], v[156:159], v[44:47]
	v_mfma_f32_16x16x32_bf16 v[40:43], v[132:135], v[156:159], v[40:43]
	v_mfma_f32_16x16x32_bf16 v[28:31], v[124:127], v[164:167], v[28:31]
	v_mfma_f32_16x16x32_bf16 v[24:27], v[132:135], v[164:167], v[24:27]
	v_mfma_f32_16x16x32_bf16 v[12:15], v[124:127], v[182:185], v[12:15]
	v_mfma_f32_16x16x32_bf16 v[8:11], v[132:135], v[182:185], v[8:11]
	s_barrier
	s_add_i32 s12, s12, s25
	s_add_u32 s68, s68, s52
	s_addc_u32 s69, s69, 0
	s_mov_b32 m0, s12
	s_nop 0
	global_load_lds_dwordx4 v192, s[68:69]
	s_add_i32 m0, s12, 0x2000
	s_nop 0
	global_load_lds_dwordx4 v172, s[68:69]
	s_waitcnt vmcnt(6)
	s_barrier
	v_mfma_f32_16x16x32_bf16 v[52:55], v[186:189], v[144:147], v[52:55]
	v_mfma_f32_16x16x32_bf16 v[48:51], v[206:209], v[144:147], v[48:51]
	v_mfma_f32_16x16x32_bf16 v[36:39], v[186:189], v[152:155], v[36:39]
	v_mfma_f32_16x16x32_bf16 v[32:35], v[206:209], v[152:155], v[32:35]
	v_mfma_f32_16x16x32_bf16 v[20:23], v[186:189], v[160:163], v[20:23]
	v_mfma_f32_16x16x32_bf16 v[16:19], v[206:209], v[160:163], v[16:19]
	v_mfma_f32_16x16x32_bf16 v[4:7], v[186:189], v[178:181], v[4:7]
	v_mfma_f32_16x16x32_bf16 v[0:3], v[206:209], v[178:181], v[0:3]
	v_mfma_f32_16x16x32_bf16 v[52:55], v[196:199], v[148:151], v[52:55]
	v_mfma_f32_16x16x32_bf16 v[48:51], v[214:217], v[148:151], v[48:51]
	v_mfma_f32_16x16x32_bf16 v[36:39], v[196:199], v[156:159], v[36:39]
	v_mfma_f32_16x16x32_bf16 v[32:35], v[214:217], v[156:159], v[32:35]
	v_mfma_f32_16x16x32_bf16 v[20:23], v[196:199], v[164:167], v[20:23]
	v_mfma_f32_16x16x32_bf16 v[16:19], v[214:217], v[164:167], v[16:19]
	v_mfma_f32_16x16x32_bf16 v[4:7], v[196:199], v[182:185], v[4:7]
	v_mfma_f32_16x16x32_bf16 v[0:3], v[214:217], v[182:185], v[0:3]
	s_add_u32 s10, s10, 0x100
	s_addc_u32 s11, s11, 0
	s_add_u32 s42, s42, 0x100
	s_addc_u32 s43, s43, 0
	s_cmp_ge_u32 s44, s33
	s_mov_b32 s12, s44
	s_barrier
.LBB0_246:
	s_add_i32 s44, s12, 2
	s_add_u32 s14, s10, 0x80
	s_addc_u32 s13, s11, 0
	s_add_i32 s45, 0, 0x10000
	ds_read_b128 v[120:123], v218 offset:0
	ds_read_b128 v[124:127], v218 offset:1024
	ds_read_b128 v[128:131], v218 offset:2048
	ds_read_b128 v[132:135], v218 offset:3072
	s_cmp_eq_u32 s36, s12
	s_cselect_b32 s12, s4, s14
	s_cselect_b32 s13, s5, s13
	s_cselect_b32 s15, s7, s43
	s_cselect_b32 s14, s6, s42
	s_add_i32 m0, s26, 0xc000
	ds_read_b128 v[144:147], v205
	ds_read_b128 v[148:151], v205 offset:1024
	ds_read_b128 v[152:155], v205 offset:2048
	ds_read_b128 v[156:159], v205 offset:3072
	ds_read_b128 v[160:163], v205 offset:4096
	ds_read_b128 v[164:167], v205 offset:5120
	ds_read_b128 v[178:181], v205 offset:6144
	ds_read_b128 v[182:185], v205 offset:7168
	global_load_lds_dwordx4 v174, s[10:11]
	s_add_i32 m0, s26, 0xe000
	s_nop 0
	global_load_lds_dwordx4 v176, s[10:11]
	s_waitcnt lgkmcnt(8)
	s_barrier
	s_waitcnt lgkmcnt(0)
	v_mfma_f32_16x16x32_bf16 v[140:143], v[120:123], v[144:147], v[140:143]
	v_mfma_f32_16x16x32_bf16 v[136:139], v[128:131], v[144:147], v[136:139]
	v_mfma_f32_16x16x32_bf16 v[108:111], v[120:123], v[152:155], v[108:111]
	v_mfma_f32_16x16x32_bf16 v[104:107], v[128:131], v[152:155], v[104:107]
	v_mfma_f32_16x16x32_bf16 v[92:95], v[120:123], v[160:163], v[92:95]
	v_mfma_f32_16x16x32_bf16 v[88:91], v[128:131], v[160:163], v[88:91]
	v_mfma_f32_16x16x32_bf16 v[76:79], v[120:123], v[178:181], v[76:79]
	v_mfma_f32_16x16x32_bf16 v[72:75], v[128:131], v[178:181], v[72:75]
	v_mfma_f32_16x16x32_bf16 v[140:143], v[124:127], v[148:151], v[140:143]
	v_mfma_f32_16x16x32_bf16 v[136:139], v[132:135], v[148:151], v[136:139]
	v_mfma_f32_16x16x32_bf16 v[108:111], v[124:127], v[156:159], v[108:111]
	v_mfma_f32_16x16x32_bf16 v[104:107], v[132:135], v[156:159], v[104:107]
	v_mfma_f32_16x16x32_bf16 v[92:95], v[124:127], v[164:167], v[92:95]
	v_mfma_f32_16x16x32_bf16 v[88:91], v[132:135], v[164:167], v[88:91]
	v_mfma_f32_16x16x32_bf16 v[76:79], v[124:127], v[182:185], v[76:79]
	v_mfma_f32_16x16x32_bf16 v[72:75], v[132:135], v[182:185], v[72:75]
	s_barrier
	s_add_i32 s46, 0, 0x14000
	s_add_i32 s45, s45, s25
	ds_read_b128 v[186:189], v218 offset:16384
	ds_read_b128 v[196:199], v218 offset:17408
	ds_read_b128 v[206:209], v218 offset:18432
	ds_read_b128 v[214:217], v218 offset:19456
	s_add_u32 s68, s14, 0x80
	s_addc_u32 s69, s15, 0
	s_mov_b32 m0, s45
	s_nop 0
	global_load_lds_dwordx4 v192, s[14:15]
	s_add_i32 m0, s45, 0x2000
	s_nop 0
	global_load_lds_dwordx4 v172, s[14:15]
	s_barrier
	s_waitcnt lgkmcnt(0)
	v_mfma_f32_16x16x32_bf16 v[116:119], v[186:189], v[144:147], v[116:119]
	v_mfma_f32_16x16x32_bf16 v[112:115], v[206:209], v[144:147], v[112:115]
	v_mfma_f32_16x16x32_bf16 v[100:103], v[186:189], v[152:155], v[100:103]
	v_mfma_f32_16x16x32_bf16 v[96:99], v[206:209], v[152:155], v[96:99]
	v_mfma_f32_16x16x32_bf16 v[84:87], v[186:189], v[160:163], v[84:87]
	v_mfma_f32_16x16x32_bf16 v[80:83], v[206:209], v[160:163], v[80:83]
	v_mfma_f32_16x16x32_bf16 v[68:71], v[186:189], v[178:181], v[68:71]
	v_mfma_f32_16x16x32_bf16 v[64:67], v[206:209], v[178:181], v[64:67]
	v_mfma_f32_16x16x32_bf16 v[116:119], v[196:199], v[148:151], v[116:119]
	v_mfma_f32_16x16x32_bf16 v[112:115], v[214:217], v[148:151], v[112:115]
	v_mfma_f32_16x16x32_bf16 v[100:103], v[196:199], v[156:159], v[100:103]
	v_mfma_f32_16x16x32_bf16 v[96:99], v[214:217], v[156:159], v[96:99]
	v_mfma_f32_16x16x32_bf16 v[84:87], v[196:199], v[164:167], v[84:87]
	v_mfma_f32_16x16x32_bf16 v[80:83], v[214:217], v[164:167], v[80:83]
	v_mfma_f32_16x16x32_bf16 v[68:71], v[196:199], v[182:185], v[68:71]
	v_mfma_f32_16x16x32_bf16 v[64:67], v[214:217], v[182:185], v[64:67]
	s_mov_b32 m0, s26
	s_add_u32 s70, s12, 0x80
	s_addc_u32 s71, s13, 0
	s_barrier
	ds_read_b128 v[144:147], v205 offset:16384
	ds_read_b128 v[148:151], v205 offset:17408
	ds_read_b128 v[152:155], v205 offset:18432
	ds_read_b128 v[156:159], v205 offset:19456
	ds_read_b128 v[160:163], v205 offset:20480
	ds_read_b128 v[164:167], v205 offset:21504
	ds_read_b128 v[178:181], v205 offset:22528
	ds_read_b128 v[182:185], v205 offset:23552
	global_load_lds_dwordx4 v168, s[12:13]
	s_mov_b32 m0, s27
	s_nop 0
	global_load_lds_dwordx4 v170, s[12:13]
	s_barrier
	s_waitcnt lgkmcnt(0)
	v_mfma_f32_16x16x32_bf16 v[60:63], v[120:123], v[144:147], v[60:63]
	v_mfma_f32_16x16x32_bf16 v[56:59], v[128:131], v[144:147], v[56:59]
	v_mfma_f32_16x16x32_bf16 v[44:47], v[120:123], v[152:155], v[44:47]
	v_mfma_f32_16x16x32_bf16 v[40:43], v[128:131], v[152:155], v[40:43]
	v_mfma_f32_16x16x32_bf16 v[28:31], v[120:123], v[160:163], v[28:31]
	v_mfma_f32_16x16x32_bf16 v[24:27], v[128:131], v[160:163], v[24:27]
	v_mfma_f32_16x16x32_bf16 v[12:15], v[120:123], v[178:181], v[12:15]
	v_mfma_f32_16x16x32_bf16 v[8:11], v[128:131], v[178:181], v[8:11]
	v_mfma_f32_16x16x32_bf16 v[60:63], v[124:127], v[148:151], v[60:63]
	v_mfma_f32_16x16x32_bf16 v[56:59], v[132:135], v[148:151], v[56:59]
	v_mfma_f32_16x16x32_bf16 v[44:47], v[124:127], v[156:159], v[44:47]
	v_mfma_f32_16x16x32_bf16 v[40:43], v[132:135], v[156:159], v[40:43]
	v_mfma_f32_16x16x32_bf16 v[28:31], v[124:127], v[164:167], v[28:31]
	v_mfma_f32_16x16x32_bf16 v[24:27], v[132:135], v[164:167], v[24:27]
	v_mfma_f32_16x16x32_bf16 v[12:15], v[124:127], v[182:185], v[12:15]
	v_mfma_f32_16x16x32_bf16 v[8:11], v[132:135], v[182:185], v[8:11]
	s_barrier
	s_add_u32 s14, s14, s52
	s_addc_u32 s15, s15, 0
	s_add_i32 s45, s46, s25
	s_mov_b32 m0, s45
	s_nop 0
	global_load_lds_dwordx4 v192, s[14:15]
	s_add_i32 m0, s45, 0x2000
	s_nop 0
	global_load_lds_dwordx4 v172, s[14:15]
	s_waitcnt vmcnt(6)
	s_barrier
	v_mfma_f32_16x16x32_bf16 v[52:55], v[186:189], v[144:147], v[52:55]
	v_mfma_f32_16x16x32_bf16 v[48:51], v[206:209], v[144:147], v[48:51]
	v_mfma_f32_16x16x32_bf16 v[36:39], v[186:189], v[152:155], v[36:39]
	v_mfma_f32_16x16x32_bf16 v[32:35], v[206:209], v[152:155], v[32:35]
	v_mfma_f32_16x16x32_bf16 v[20:23], v[186:189], v[160:163], v[20:23]
	v_mfma_f32_16x16x32_bf16 v[16:19], v[206:209], v[160:163], v[16:19]
	v_mfma_f32_16x16x32_bf16 v[4:7], v[186:189], v[178:181], v[4:7]
	v_mfma_f32_16x16x32_bf16 v[0:3], v[206:209], v[178:181], v[0:3]
	v_mfma_f32_16x16x32_bf16 v[52:55], v[196:199], v[148:151], v[52:55]
	v_mfma_f32_16x16x32_bf16 v[48:51], v[214:217], v[148:151], v[48:51]
	v_mfma_f32_16x16x32_bf16 v[36:39], v[196:199], v[156:159], v[36:39]
	v_mfma_f32_16x16x32_bf16 v[32:35], v[214:217], v[156:159], v[32:35]
	v_mfma_f32_16x16x32_bf16 v[20:23], v[196:199], v[164:167], v[20:23]
	v_mfma_f32_16x16x32_bf16 v[16:19], v[214:217], v[164:167], v[16:19]
	v_mfma_f32_16x16x32_bf16 v[4:7], v[196:199], v[182:185], v[4:7]
	v_mfma_f32_16x16x32_bf16 v[0:3], v[214:217], v[182:185], v[0:3]
	s_add_i32 s14, 0, 0x18000
	s_barrier
	ds_read_b128 v[120:123], v218 offset:32768
	ds_read_b128 v[124:127], v218 offset:33792
	ds_read_b128 v[128:131], v218 offset:34816
	ds_read_b128 v[132:135], v218 offset:35840
	s_add_u32 s12, s12, s52
	s_addc_u32 s13, s13, 0
	s_mov_b32 m0, s28
	ds_read_b128 v[144:147], v205 offset:32768
	ds_read_b128 v[148:151], v205 offset:33792
	ds_read_b128 v[152:155], v205 offset:34816
	ds_read_b128 v[156:159], v205 offset:35840
	ds_read_b128 v[160:163], v205 offset:36864
	ds_read_b128 v[164:167], v205 offset:37888
	ds_read_b128 v[178:181], v205 offset:38912
	ds_read_b128 v[182:185], v205 offset:39936
	global_load_lds_dwordx4 v168, s[12:13]
	s_mov_b32 m0, s29
	s_nop 0
	global_load_lds_dwordx4 v170, s[12:13]
	s_waitcnt lgkmcnt(8)
	s_barrier
	s_waitcnt lgkmcnt(0)
	v_mfma_f32_16x16x32_bf16 v[140:143], v[120:123], v[144:147], v[140:143]
	v_mfma_f32_16x16x32_bf16 v[136:139], v[128:131], v[144:147], v[136:139]
	v_mfma_f32_16x16x32_bf16 v[108:111], v[120:123], v[152:155], v[108:111]
	v_mfma_f32_16x16x32_bf16 v[104:107], v[128:131], v[152:155], v[104:107]
	v_mfma_f32_16x16x32_bf16 v[92:95], v[120:123], v[160:163], v[92:95]
	v_mfma_f32_16x16x32_bf16 v[88:91], v[128:131], v[160:163], v[88:91]
	v_mfma_f32_16x16x32_bf16 v[76:79], v[120:123], v[178:181], v[76:79]
	v_mfma_f32_16x16x32_bf16 v[72:75], v[128:131], v[178:181], v[72:75]
	v_mfma_f32_16x16x32_bf16 v[140:143], v[124:127], v[148:151], v[140:143]
	v_mfma_f32_16x16x32_bf16 v[136:139], v[132:135], v[148:151], v[136:139]
	v_mfma_f32_16x16x32_bf16 v[108:111], v[124:127], v[156:159], v[108:111]
	v_mfma_f32_16x16x32_bf16 v[104:107], v[132:135], v[156:159], v[104:107]
	v_mfma_f32_16x16x32_bf16 v[92:95], v[124:127], v[164:167], v[92:95]
	v_mfma_f32_16x16x32_bf16 v[88:91], v[132:135], v[164:167], v[88:91]
	v_mfma_f32_16x16x32_bf16 v[76:79], v[124:127], v[182:185], v[76:79]
	v_mfma_f32_16x16x32_bf16 v[72:75], v[132:135], v[182:185], v[72:75]
	s_barrier
	s_add_i32 s12, 0, 0x1c000
	s_add_i32 s13, s14, s25
	s_mov_b32 m0, s13
	ds_read_b128 v[186:189], v218 offset:49152
	ds_read_b128 v[196:199], v218 offset:50176
	ds_read_b128 v[206:209], v218 offset:51200
	ds_read_b128 v[214:217], v218 offset:52224
	global_load_lds_dwordx4 v192, s[68:69]
	s_add_i32 m0, s13, 0x2000
	s_nop 0
	global_load_lds_dwordx4 v172, s[68:69]
	s_barrier
	s_waitcnt lgkmcnt(0)
	v_mfma_f32_16x16x32_bf16 v[116:119], v[186:189], v[144:147], v[116:119]
	v_mfma_f32_16x16x32_bf16 v[112:115], v[206:209], v[144:147], v[112:115]
	v_mfma_f32_16x16x32_bf16 v[100:103], v[186:189], v[152:155], v[100:103]
	v_mfma_f32_16x16x32_bf16 v[96:99], v[206:209], v[152:155], v[96:99]
	v_mfma_f32_16x16x32_bf16 v[84:87], v[186:189], v[160:163], v[84:87]
	v_mfma_f32_16x16x32_bf16 v[80:83], v[206:209], v[160:163], v[80:83]
	v_mfma_f32_16x16x32_bf16 v[68:71], v[186:189], v[178:181], v[68:71]
	v_mfma_f32_16x16x32_bf16 v[64:67], v[206:209], v[178:181], v[64:67]
	v_mfma_f32_16x16x32_bf16 v[116:119], v[196:199], v[148:151], v[116:119]
	v_mfma_f32_16x16x32_bf16 v[112:115], v[214:217], v[148:151], v[112:115]
	v_mfma_f32_16x16x32_bf16 v[100:103], v[196:199], v[156:159], v[100:103]
	v_mfma_f32_16x16x32_bf16 v[96:99], v[214:217], v[156:159], v[96:99]
	v_mfma_f32_16x16x32_bf16 v[84:87], v[196:199], v[164:167], v[84:87]
	v_mfma_f32_16x16x32_bf16 v[80:83], v[214:217], v[164:167], v[80:83]
	v_mfma_f32_16x16x32_bf16 v[68:71], v[196:199], v[182:185], v[68:71]
	v_mfma_f32_16x16x32_bf16 v[64:67], v[214:217], v[182:185], v[64:67]
	s_mov_b32 m0, s34
	s_barrier
	ds_read_b128 v[144:147], v205 offset:49152
	ds_read_b128 v[148:151], v205 offset:50176
	ds_read_b128 v[152:155], v205 offset:51200
	ds_read_b128 v[156:159], v205 offset:52224
	ds_read_b128 v[160:163], v205 offset:53248
	ds_read_b128 v[164:167], v205 offset:54272
	ds_read_b128 v[178:181], v205 offset:55296
	ds_read_b128 v[182:185], v205 offset:56320
	global_load_lds_dwordx4 v168, s[70:71]
	s_mov_b32 m0, s35
	s_nop 0
	global_load_lds_dwordx4 v170, s[70:71]
	s_barrier
	s_waitcnt lgkmcnt(0)
	v_mfma_f32_16x16x32_bf16 v[60:63], v[120:123], v[144:147], v[60:63]
	v_mfma_f32_16x16x32_bf16 v[56:59], v[128:131], v[144:147], v[56:59]
	v_mfma_f32_16x16x32_bf16 v[44:47], v[120:123], v[152:155], v[44:47]
	v_mfma_f32_16x16x32_bf16 v[40:43], v[128:131], v[152:155], v[40:43]
	v_mfma_f32_16x16x32_bf16 v[28:31], v[120:123], v[160:163], v[28:31]
	v_mfma_f32_16x16x32_bf16 v[24:27], v[128:131], v[160:163], v[24:27]
	v_mfma_f32_16x16x32_bf16 v[12:15], v[120:123], v[178:181], v[12:15]
	v_mfma_f32_16x16x32_bf16 v[8:11], v[128:131], v[178:181], v[8:11]
	v_mfma_f32_16x16x32_bf16 v[60:63], v[124:127], v[148:151], v[60:63]
	v_mfma_f32_16x16x32_bf16 v[56:59], v[132:135], v[148:151], v[56:59]
	v_mfma_f32_16x16x32_bf16 v[44:47], v[124:127], v[156:159], v[44:47]
	v_mfma_f32_16x16x32_bf16 v[40:43], v[132:135], v[156:159], v[40:43]
	v_mfma_f32_16x16x32_bf16 v[28:31], v[124:127], v[164:167], v[28:31]
	v_mfma_f32_16x16x32_bf16 v[24:27], v[132:135], v[164:167], v[24:27]
	v_mfma_f32_16x16x32_bf16 v[12:15], v[124:127], v[182:185], v[12:15]
	v_mfma_f32_16x16x32_bf16 v[8:11], v[132:135], v[182:185], v[8:11]
	s_barrier
	s_add_i32 s12, s12, s25
	s_add_u32 s68, s68, s52
	s_addc_u32 s69, s69, 0
	s_mov_b32 m0, s12
	s_nop 0
	global_load_lds_dwordx4 v192, s[68:69]
	s_add_i32 m0, s12, 0x2000
	s_nop 0
	global_load_lds_dwordx4 v172, s[68:69]
	s_waitcnt vmcnt(6)
	s_barrier
	v_mfma_f32_16x16x32_bf16 v[52:55], v[186:189], v[144:147], v[52:55]
	v_mfma_f32_16x16x32_bf16 v[48:51], v[206:209], v[144:147], v[48:51]
	v_mfma_f32_16x16x32_bf16 v[36:39], v[186:189], v[152:155], v[36:39]
	v_mfma_f32_16x16x32_bf16 v[32:35], v[206:209], v[152:155], v[32:35]
	v_mfma_f32_16x16x32_bf16 v[20:23], v[186:189], v[160:163], v[20:23]
	v_mfma_f32_16x16x32_bf16 v[16:19], v[206:209], v[160:163], v[16:19]
	v_mfma_f32_16x16x32_bf16 v[4:7], v[186:189], v[178:181], v[4:7]
	v_mfma_f32_16x16x32_bf16 v[0:3], v[206:209], v[178:181], v[0:3]
	v_mfma_f32_16x16x32_bf16 v[52:55], v[196:199], v[148:151], v[52:55]
	v_mfma_f32_16x16x32_bf16 v[48:51], v[214:217], v[148:151], v[48:51]
	v_mfma_f32_16x16x32_bf16 v[36:39], v[196:199], v[156:159], v[36:39]
	v_mfma_f32_16x16x32_bf16 v[32:35], v[214:217], v[156:159], v[32:35]
	v_mfma_f32_16x16x32_bf16 v[20:23], v[196:199], v[164:167], v[20:23]
	v_mfma_f32_16x16x32_bf16 v[16:19], v[214:217], v[164:167], v[16:19]
	v_mfma_f32_16x16x32_bf16 v[4:7], v[196:199], v[182:185], v[4:7]
	v_mfma_f32_16x16x32_bf16 v[0:3], v[214:217], v[182:185], v[0:3]
	s_add_u32 s10, s10, 0x100
	s_addc_u32 s11, s11, 0
	s_add_u32 s42, s42, 0x100
	s_addc_u32 s43, s43, 0
	s_cmp_ge_u32 s44, s33
	s_mov_b32 s12, s44
	s_barrier
	s_cbranch_scc0 .LBB0_246
	v_lshl_or_b32 v144, s41, 8, v204
	s_ashr_i32 s10, s40, 4
	s_mul_hi_i32 s11, s10, 0xc000
	s_mul_i32 s10, s10, 0xc000
	v_ashrrev_i32_e32 v145, 31, v144
	v_lshl_add_u32 v146, s40, 8, v190
	s_add_u32 s10, s30, s10
	v_lshlrev_b64 v[178:179], 1, v[144:145]
	v_ashrrev_i32_e32 v147, 31, v146
	s_addc_u32 s11, s31, s11
	v_lshl_add_u64 v[180:181], s[2:3], 0, v[178:179]
	v_lshlrev_b64 v[182:183], 12, v[146:147]
	v_lshl_add_u64 v[124:125], v[144:145], 2, s[10:11]
	v_lshl_add_u64 v[144:145], v[180:181], 0, v[182:183]
	global_load_dwordx4 v[128:131], v[124:125], off offset:16
	global_load_dwordx4 v[132:135], v[124:125], off
	global_load_dwordx4 v[120:123], v[124:125], off offset:528
	s_nop 0
	global_load_dwordx4 v[124:127], v[124:125], off offset:512
	s_nop 0
	global_load_dwordx4 v[196:199], v[144:145], off
	global_load_dwordx4 v[206:209], v[144:145], off offset:256
	v_or_b32_e32 v144, 16, v146
	v_ashrrev_i32_e32 v145, 31, v144
	v_lshlrev_b64 v[188:189], 12, v[144:145]
	v_lshl_add_u64 v[144:145], v[180:181], 0, v[188:189]
	global_load_dwordx4 v[164:167], v[144:145], off
	global_load_dwordx4 v[160:163], v[144:145], off offset:256
	v_or_b32_e32 v144, 32, v146
	v_ashrrev_i32_e32 v145, 31, v144
	v_lshlrev_b64 v[186:187], 12, v[144:145]
	v_lshl_add_u64 v[144:145], v[180:181], 0, v[186:187]
	global_load_dwordx4 v[156:159], v[144:145], off
	global_load_dwordx4 v[152:155], v[144:145], off offset:256
	v_or_b32_e32 v144, 48, v146
	v_ashrrev_i32_e32 v145, 31, v144
	v_lshlrev_b64 v[184:185], 12, v[144:145]
	v_lshl_add_u64 v[144:145], v[180:181], 0, v[184:185]
	global_load_dwordx4 v[148:151], v[144:145], off
	s_nop 0
	global_load_dwordx4 v[144:147], v[144:145], off offset:256
	s_mov_b64 s[10:11], 0x80000
	s_and_b64 vcc, exec, s[0:1]
	s_mov_b32 s41, s38
	s_mov_b32 s40, s39
	s_mov_b64 s[12:13], s[6:7]
	v_readlane_b32 s14, v254, 21
	s_movk_i32 s15, 0x2000
	s_waitcnt vmcnt(0)
	v_lshlrev_b32_e32 v210, 16, v196
	v_and_b32_e32 v211, 0xffff0000, v196
	v_lshlrev_b32_e32 v196, 16, v197
	v_and_b32_e32 v197, 0xffff0000, v197
	v_lshlrev_b32_e32 v214, 16, v198
	v_and_b32_e32 v215, 0xffff0000, v198
	v_lshlrev_b32_e32 v198, 16, v199
	v_and_b32_e32 v199, 0xffff0000, v199
	v_pk_fma_f32 v[140:141], v[140:141], v[132:133], v[210:211]
	v_pk_fma_f32 v[142:143], v[142:143], v[134:135], v[196:197]
	v_pk_fma_f32 v[196:197], v[138:139], v[130:131], v[198:199]
	v_pk_fma_f32 v[138:139], v[136:137], v[128:129], v[214:215]
	v_cvt_pk_bf16_f32 v136, v140, v141
	v_lshl_add_u64 v[140:141], s[8:9], 0, v[182:183]
	v_cvt_pk_bf16_f32 v137, v142, v143
	v_cvt_pk_bf16_f32 v138, v138, v139
	v_cvt_pk_bf16_f32 v139, v196, v197
	v_lshl_add_u64 v[140:141], v[140:141], 0, v[178:179]
	global_store_dwordx4 v[140:141], v[136:139], off
	v_lshlrev_b32_e32 v142, 16, v208
	v_and_b32_e32 v143, 0xffff0000, v208
	v_lshlrev_b32_e32 v136, 16, v206
	v_and_b32_e32 v137, 0xffff0000, v206
	v_lshlrev_b32_e32 v138, 16, v207
	v_and_b32_e32 v139, 0xffff0000, v207
	v_lshlrev_b32_e32 v196, 16, v209
	v_and_b32_e32 v197, 0xffff0000, v209
	v_pk_fma_f32 v[118:119], v[118:119], v[126:127], v[138:139]
	v_pk_fma_f32 v[116:117], v[116:117], v[124:125], v[136:137]
	v_pk_fma_f32 v[136:137], v[114:115], v[122:123], v[196:197]
	v_pk_fma_f32 v[114:115], v[112:113], v[120:121], v[142:143]
	v_cvt_pk_bf16_f32 v112, v116, v117
	v_cvt_pk_bf16_f32 v113, v118, v119
	v_lshlrev_b32_e32 v116, 16, v166
	v_cvt_pk_bf16_f32 v114, v114, v115
	v_cvt_pk_bf16_f32 v115, v136, v137
	global_store_dwordx4 v[140:141], v[112:115], off offset:256
	v_and_b32_e32 v117, 0xffff0000, v166
	v_lshlrev_b32_e32 v118, 16, v167
	v_lshlrev_b32_e32 v112, 16, v164
	v_and_b32_e32 v113, 0xffff0000, v164
	v_and_b32_e32 v119, 0xffff0000, v167
	v_pk_fma_f32 v[108:109], v[108:109], v[132:133], v[112:113]
	v_lshlrev_b32_e32 v114, 16, v165
	v_and_b32_e32 v115, 0xffff0000, v165
	v_pk_fma_f32 v[112:113], v[106:107], v[130:131], v[118:119]
	v_pk_fma_f32 v[106:107], v[104:105], v[128:129], v[116:117]
	v_cvt_pk_bf16_f32 v104, v108, v109
	v_lshl_add_u64 v[108:109], s[8:9], 0, v[188:189]
	v_pk_fma_f32 v[110:111], v[110:111], v[134:135], v[114:115]
	v_lshl_add_u64 v[108:109], v[108:109], 0, v[178:179]
	v_cvt_pk_bf16_f32 v105, v110, v111
	v_cvt_pk_bf16_f32 v106, v106, v107
	v_cvt_pk_bf16_f32 v107, v112, v113
	global_store_dwordx4 v[108:109], v[104:107], off
	v_lshlrev_b32_e32 v110, 16, v162
	v_and_b32_e32 v111, 0xffff0000, v162
	v_lshlrev_b32_e32 v104, 16, v160
	v_and_b32_e32 v105, 0xffff0000, v160
	v_lshlrev_b32_e32 v106, 16, v161
	v_and_b32_e32 v107, 0xffff0000, v161
	v_lshlrev_b32_e32 v112, 16, v163
	v_and_b32_e32 v113, 0xffff0000, v163
	v_pk_fma_f32 v[102:103], v[102:103], v[126:127], v[106:107]
	v_pk_fma_f32 v[100:101], v[100:101], v[124:125], v[104:105]
	v_pk_fma_f32 v[104:105], v[98:99], v[122:123], v[112:113]
	v_pk_fma_f32 v[98:99], v[96:97], v[120:121], v[110:111]
	v_cvt_pk_bf16_f32 v96, v100, v101
	v_cvt_pk_bf16_f32 v97, v102, v103
	v_lshlrev_b32_e32 v100, 16, v158
	v_cvt_pk_bf16_f32 v98, v98, v99
	v_cvt_pk_bf16_f32 v99, v104, v105
	global_store_dwordx4 v[108:109], v[96:99], off offset:256
	v_and_b32_e32 v101, 0xffff0000, v158
	v_lshlrev_b32_e32 v102, 16, v159
	v_lshlrev_b32_e32 v96, 16, v156
	v_and_b32_e32 v97, 0xffff0000, v156
	v_and_b32_e32 v103, 0xffff0000, v159
	v_pk_fma_f32 v[92:93], v[92:93], v[132:133], v[96:97]
	v_lshlrev_b32_e32 v98, 16, v157
	v_and_b32_e32 v99, 0xffff0000, v157
	v_pk_fma_f32 v[96:97], v[90:91], v[130:131], v[102:103]
	v_pk_fma_f32 v[90:91], v[88:89], v[128:129], v[100:101]
	v_cvt_pk_bf16_f32 v88, v92, v93
	v_lshl_add_u64 v[92:93], s[8:9], 0, v[186:187]
	v_pk_fma_f32 v[94:95], v[94:95], v[134:135], v[98:99]
	v_lshl_add_u64 v[92:93], v[92:93], 0, v[178:179]
	v_cvt_pk_bf16_f32 v89, v94, v95
	v_cvt_pk_bf16_f32 v90, v90, v91
	v_cvt_pk_bf16_f32 v91, v96, v97
	global_store_dwordx4 v[92:93], v[88:91], off
	v_lshlrev_b32_e32 v94, 16, v154
	v_and_b32_e32 v95, 0xffff0000, v154
	v_lshlrev_b32_e32 v88, 16, v152
	v_and_b32_e32 v89, 0xffff0000, v152
	v_lshlrev_b32_e32 v90, 16, v153
	v_and_b32_e32 v91, 0xffff0000, v153
	v_lshlrev_b32_e32 v96, 16, v155
	v_and_b32_e32 v97, 0xffff0000, v155
	v_pk_fma_f32 v[86:87], v[86:87], v[126:127], v[90:91]
	v_pk_fma_f32 v[84:85], v[84:85], v[124:125], v[88:89]
	v_pk_fma_f32 v[88:89], v[82:83], v[122:123], v[96:97]
	v_pk_fma_f32 v[82:83], v[80:81], v[120:121], v[94:95]
	v_cvt_pk_bf16_f32 v80, v84, v85
	v_cvt_pk_bf16_f32 v81, v86, v87
	v_lshlrev_b32_e32 v84, 16, v150
	v_cvt_pk_bf16_f32 v82, v82, v83
	v_cvt_pk_bf16_f32 v83, v88, v89
	global_store_dwordx4 v[92:93], v[80:83], off offset:256
	v_and_b32_e32 v85, 0xffff0000, v150
	v_lshlrev_b32_e32 v86, 16, v151
	v_lshlrev_b32_e32 v80, 16, v148
	v_and_b32_e32 v81, 0xffff0000, v148
	v_and_b32_e32 v87, 0xffff0000, v151
	v_pk_fma_f32 v[76:77], v[76:77], v[132:133], v[80:81]
	v_lshlrev_b32_e32 v82, 16, v149
	v_and_b32_e32 v83, 0xffff0000, v149
	v_pk_fma_f32 v[80:81], v[74:75], v[130:131], v[86:87]
	v_pk_fma_f32 v[74:75], v[72:73], v[128:129], v[84:85]
	v_cvt_pk_bf16_f32 v72, v76, v77
	v_lshl_add_u64 v[76:77], s[8:9], 0, v[184:185]
	v_pk_fma_f32 v[78:79], v[78:79], v[134:135], v[82:83]
	v_lshl_add_u64 v[76:77], v[76:77], 0, v[178:179]
	v_cvt_pk_bf16_f32 v73, v78, v79
	v_cvt_pk_bf16_f32 v74, v74, v75
	v_cvt_pk_bf16_f32 v75, v80, v81
	global_store_dwordx4 v[76:77], v[72:75], off
	v_lshlrev_b32_e32 v78, 16, v146
	v_and_b32_e32 v79, 0xffff0000, v146
	v_lshlrev_b32_e32 v72, 16, v144
	v_and_b32_e32 v73, 0xffff0000, v144
	v_lshlrev_b32_e32 v74, 16, v145
	v_and_b32_e32 v75, 0xffff0000, v145
	v_lshlrev_b32_e32 v80, 16, v147
	v_and_b32_e32 v81, 0xffff0000, v147
	v_pk_fma_f32 v[70:71], v[70:71], v[126:127], v[74:75]
	v_pk_fma_f32 v[68:69], v[68:69], v[124:125], v[72:73]
	v_pk_fma_f32 v[72:73], v[66:67], v[122:123], v[80:81]
	v_pk_fma_f32 v[66:67], v[64:65], v[120:121], v[78:79]
	v_cvt_pk_bf16_f32 v64, v68, v69
	v_cvt_pk_bf16_f32 v65, v70, v71
	v_lshl_add_u64 v[98:99], v[182:183], 0, s[10:11]
	v_cvt_pk_bf16_f32 v66, v66, v67
	v_cvt_pk_bf16_f32 v67, v72, v73
	global_store_dwordx4 v[76:77], v[64:67], off offset:256
	s_mov_b64 s[10:11], 0x90000
	v_lshl_add_u64 v[100:101], v[182:183], 0, s[10:11]
	v_lshl_add_u64 v[64:65], v[180:181], 0, v[98:99]
	global_load_dwordx4 v[74:77], v[64:65], off
	global_load_dwordx4 v[78:81], v[64:65], off offset:256
	v_lshl_add_u64 v[64:65], v[180:181], 0, v[100:101]
	global_load_dwordx4 v[82:85], v[64:65], off
	global_load_dwordx4 v[86:89], v[64:65], off offset:256
	s_mov_b64 s[10:11], 0xa0000
	v_lshl_add_u64 v[102:103], v[182:183], 0, s[10:11]
	v_lshl_add_u64 v[64:65], v[180:181], 0, v[102:103]
	global_load_dwordx4 v[90:93], v[64:65], off
	global_load_dwordx4 v[94:97], v[64:65], off offset:256
	s_mov_b64 s[10:11], 0xb0000
	v_lshl_add_u64 v[72:73], v[182:183], 0, s[10:11]
	v_lshl_add_u64 v[64:65], v[180:181], 0, v[72:73]
	global_load_dwordx4 v[68:71], v[64:65], off
	s_nop 0
	global_load_dwordx4 v[64:67], v[64:65], off offset:256
	s_mov_b64 s[10:11], s[4:5]
	s_waitcnt vmcnt(0)
	v_lshlrev_b32_e32 v104, 16, v74
	v_and_b32_e32 v105, 0xffff0000, v74
	v_lshlrev_b32_e32 v74, 16, v75
	v_and_b32_e32 v75, 0xffff0000, v75
	v_lshlrev_b32_e32 v106, 16, v76
	v_and_b32_e32 v107, 0xffff0000, v76
	v_lshlrev_b32_e32 v76, 16, v77
	v_and_b32_e32 v77, 0xffff0000, v77
	v_pk_fma_f32 v[60:61], v[60:61], v[132:133], v[104:105]
	v_pk_fma_f32 v[62:63], v[62:63], v[134:135], v[74:75]
	v_pk_fma_f32 v[74:75], v[58:59], v[130:131], v[76:77]
	v_pk_fma_f32 v[58:59], v[56:57], v[128:129], v[106:107]
	v_cvt_pk_bf16_f32 v56, v60, v61
	v_lshl_add_u64 v[60:61], s[8:9], 0, v[98:99]
	v_cvt_pk_bf16_f32 v57, v62, v63
	v_cvt_pk_bf16_f32 v58, v58, v59
	v_cvt_pk_bf16_f32 v59, v74, v75
	v_lshl_add_u64 v[60:61], v[60:61], 0, v[178:179]
	global_store_dwordx4 v[60:61], v[56:59], off
	v_lshlrev_b32_e32 v62, 16, v80
	v_and_b32_e32 v63, 0xffff0000, v80
	v_lshlrev_b32_e32 v56, 16, v78
	v_and_b32_e32 v57, 0xffff0000, v78
	v_lshlrev_b32_e32 v58, 16, v79
	v_and_b32_e32 v59, 0xffff0000, v79
	v_lshlrev_b32_e32 v74, 16, v81
	v_and_b32_e32 v75, 0xffff0000, v81
	v_pk_fma_f32 v[54:55], v[54:55], v[126:127], v[58:59]
	v_pk_fma_f32 v[52:53], v[52:53], v[124:125], v[56:57]
	v_pk_fma_f32 v[56:57], v[50:51], v[122:123], v[74:75]
	v_pk_fma_f32 v[50:51], v[48:49], v[120:121], v[62:63]
	v_cvt_pk_bf16_f32 v48, v52, v53
	v_cvt_pk_bf16_f32 v49, v54, v55
	v_lshlrev_b32_e32 v52, 16, v84
	v_cvt_pk_bf16_f32 v50, v50, v51
	v_cvt_pk_bf16_f32 v51, v56, v57
	global_store_dwordx4 v[60:61], v[48:51], off offset:256
	v_and_b32_e32 v53, 0xffff0000, v84
	v_lshlrev_b32_e32 v54, 16, v85
	v_lshlrev_b32_e32 v48, 16, v82
	v_and_b32_e32 v49, 0xffff0000, v82
	v_and_b32_e32 v55, 0xffff0000, v85
	v_pk_fma_f32 v[44:45], v[44:45], v[132:133], v[48:49]
	v_lshlrev_b32_e32 v50, 16, v83
	v_and_b32_e32 v51, 0xffff0000, v83
	v_pk_fma_f32 v[48:49], v[42:43], v[130:131], v[54:55]
	v_pk_fma_f32 v[42:43], v[40:41], v[128:129], v[52:53]
	v_cvt_pk_bf16_f32 v40, v44, v45
	v_lshl_add_u64 v[44:45], s[8:9], 0, v[100:101]
	v_pk_fma_f32 v[46:47], v[46:47], v[134:135], v[50:51]
	v_lshl_add_u64 v[44:45], v[44:45], 0, v[178:179]
	v_cvt_pk_bf16_f32 v41, v46, v47
	v_cvt_pk_bf16_f32 v42, v42, v43
	v_cvt_pk_bf16_f32 v43, v48, v49
	global_store_dwordx4 v[44:45], v[40:43], off
	v_lshlrev_b32_e32 v46, 16, v88
	v_and_b32_e32 v47, 0xffff0000, v88
	v_lshlrev_b32_e32 v40, 16, v86
	v_and_b32_e32 v41, 0xffff0000, v86
	v_lshlrev_b32_e32 v42, 16, v87
	v_and_b32_e32 v43, 0xffff0000, v87
	v_lshlrev_b32_e32 v48, 16, v89
	v_and_b32_e32 v49, 0xffff0000, v89
	v_pk_fma_f32 v[38:39], v[38:39], v[126:127], v[42:43]
	v_pk_fma_f32 v[36:37], v[36:37], v[124:125], v[40:41]
	v_pk_fma_f32 v[40:41], v[34:35], v[122:123], v[48:49]
	v_pk_fma_f32 v[34:35], v[32:33], v[120:121], v[46:47]
	v_cvt_pk_bf16_f32 v32, v36, v37
	v_cvt_pk_bf16_f32 v33, v38, v39
	v_lshlrev_b32_e32 v36, 16, v92
	v_cvt_pk_bf16_f32 v34, v34, v35
	v_cvt_pk_bf16_f32 v35, v40, v41
	global_store_dwordx4 v[44:45], v[32:35], off offset:256
	v_and_b32_e32 v37, 0xffff0000, v92
	v_lshlrev_b32_e32 v38, 16, v93
	v_lshlrev_b32_e32 v32, 16, v90
	v_and_b32_e32 v33, 0xffff0000, v90
	v_and_b32_e32 v39, 0xffff0000, v93
	v_pk_fma_f32 v[28:29], v[28:29], v[132:133], v[32:33]
	v_lshlrev_b32_e32 v34, 16, v91
	v_and_b32_e32 v35, 0xffff0000, v91
	v_pk_fma_f32 v[32:33], v[26:27], v[130:131], v[38:39]
	v_pk_fma_f32 v[26:27], v[24:25], v[128:129], v[36:37]
	v_cvt_pk_bf16_f32 v24, v28, v29
	v_lshl_add_u64 v[28:29], s[8:9], 0, v[102:103]
	v_pk_fma_f32 v[30:31], v[30:31], v[134:135], v[34:35]
	v_lshl_add_u64 v[28:29], v[28:29], 0, v[178:179]
	v_cvt_pk_bf16_f32 v25, v30, v31
	v_cvt_pk_bf16_f32 v26, v26, v27
	v_cvt_pk_bf16_f32 v27, v32, v33
	global_store_dwordx4 v[28:29], v[24:27], off
	v_lshlrev_b32_e32 v30, 16, v96
	v_and_b32_e32 v31, 0xffff0000, v96
	v_lshlrev_b32_e32 v24, 16, v94
	v_and_b32_e32 v25, 0xffff0000, v94
	v_lshlrev_b32_e32 v26, 16, v95
	v_and_b32_e32 v27, 0xffff0000, v95
	v_lshlrev_b32_e32 v32, 16, v97
	v_and_b32_e32 v33, 0xffff0000, v97
	v_pk_fma_f32 v[22:23], v[22:23], v[126:127], v[26:27]
	v_pk_fma_f32 v[20:21], v[20:21], v[124:125], v[24:25]
	v_pk_fma_f32 v[24:25], v[18:19], v[122:123], v[32:33]
	v_pk_fma_f32 v[18:19], v[16:17], v[120:121], v[30:31]
	v_cvt_pk_bf16_f32 v16, v20, v21
	v_cvt_pk_bf16_f32 v17, v22, v23
	v_lshlrev_b32_e32 v20, 16, v70
	v_cvt_pk_bf16_f32 v18, v18, v19
	v_cvt_pk_bf16_f32 v19, v24, v25
	global_store_dwordx4 v[28:29], v[16:19], off offset:256
	v_and_b32_e32 v21, 0xffff0000, v70
	v_lshlrev_b32_e32 v22, 16, v71
	v_lshlrev_b32_e32 v16, 16, v68
	v_and_b32_e32 v17, 0xffff0000, v68
	v_and_b32_e32 v23, 0xffff0000, v71
	v_pk_fma_f32 v[12:13], v[12:13], v[132:133], v[16:17]
	v_lshlrev_b32_e32 v18, 16, v69
	v_and_b32_e32 v19, 0xffff0000, v69
	v_pk_fma_f32 v[16:17], v[10:11], v[130:131], v[22:23]
	v_pk_fma_f32 v[10:11], v[8:9], v[128:129], v[20:21]
	v_cvt_pk_bf16_f32 v8, v12, v13
	v_lshl_add_u64 v[12:13], s[8:9], 0, v[72:73]
	v_pk_fma_f32 v[14:15], v[14:15], v[134:135], v[18:19]
	v_lshl_add_u64 v[12:13], v[12:13], 0, v[178:179]
	v_cvt_pk_bf16_f32 v9, v14, v15
	v_cvt_pk_bf16_f32 v10, v10, v11
	v_cvt_pk_bf16_f32 v11, v16, v17
	global_store_dwordx4 v[12:13], v[8:11], off
	v_lshlrev_b32_e32 v14, 16, v66
	v_and_b32_e32 v15, 0xffff0000, v66
	v_lshlrev_b32_e32 v8, 16, v64
	v_and_b32_e32 v9, 0xffff0000, v64
	v_lshlrev_b32_e32 v16, 16, v67
	v_and_b32_e32 v17, 0xffff0000, v67
	v_lshlrev_b32_e32 v10, 16, v65
	v_and_b32_e32 v11, 0xffff0000, v65
	v_pk_fma_f32 v[4:5], v[4:5], v[124:125], v[8:9]
	v_pk_fma_f32 v[8:9], v[2:3], v[122:123], v[16:17]
	v_pk_fma_f32 v[2:3], v[0:1], v[120:121], v[14:15]
	v_pk_fma_f32 v[6:7], v[6:7], v[126:127], v[10:11]
	v_cvt_pk_bf16_f32 v0, v4, v5
	s_nop 0
	v_cvt_pk_bf16_f32 v1, v6, v7
	v_cvt_pk_bf16_f32 v2, v2, v3
	v_cvt_pk_bf16_f32 v3, v8, v9
	global_store_dwordx4 v[12:13], v[0:3], off offset:256
	s_cbranch_vccz .LBB0_235
	s_waitcnt vmcnt(0)
	s_cmpk_gt_u32 s16, 0xff
	s_cbranch_scc1 .LBB0_250
	s_barrier
